# attention: gate_b rows for the unit epilogue are loaded at the unit prologue (held in 16 VGPRs across the key loop) so the epilogue has no memory round trip
# speedup vs baseline: 1.0246x; 1.0042x over previous
; __device__ __forceinline__ float sigm(float x) { return __builtin_amdgcn_rcpf(1.f + __builtin_amdgcn_exp2f(-1.4426950408889634f * x)); }
; __device__ __forceinline__ u32x4 pack8(const f32x4 a, const f32x4 b) { u32x4 w; w.x = cvt_pk_bf16(a[0], a[1]); w.y = cvt_pk_bf16(a[2], a[3]); w.z = cvt_pk_bf16(b[0], b[1]); w.w = cvt_pk_bf16(b[2], b[3]); return w; }
; #define LAS __attribute__((address_space(3)))
;     ...
;     LAS float* stg = (LAS float*)(lds + AT_STG + wid * AT_STG_W);
; #pragma unroll
;     for (int g4 = 0; g4 < 4; ++g4) {
;         *(LAS f32x4*)(stg + r32 * 68 + 8 * g4 + 4 * hi) = (f32x4){o0[4 * g4], o0[4 * g4 + 1], o0[4 * g4 + 2], o0[4 * g4 + 3]};
;         *(LAS f32x4*)(stg + r32 * 68 + 32 + 8 * g4 + 4 * hi) = (f32x4){o1[4 * g4], o1[4 * g4 + 1], o1[4 * g4 + 2], o1[4 * g4 + 3]};
;     }
;     asm volatile("s_waitcnt lgkmcnt(0)" ::: "memory");
; #pragma unroll
;     for (int i = 0; i < 4; ++i) {
;         const int row = i * 8 + (lane >> 3), ch = lane & 7;
;         f32x4 a0 = *(const LAS f32x4*)(stg + row * 68 + ch * 8), a1 = *(const LAS f32x4*)(stg + row * 68 + ch * 8 + 4);
;         const size_t tok = rowbase + qw + row;
;         const u32x4 gw_ = *(const u32x4*)(GBb + tok * 1024 + h * HD + ch * 8);
;         f32x4 g0, g1; pg8::unpack8(gw_, g0, g1);
; #pragma unroll
;         for (int e = 0; e < 4; ++e) { a0[e] *= g0[e] * pg8::sigm(g0[e]); a1[e] *= g1[e] * pg8::sigm(g1[e]); }
;         if (!dry) *(u32x4*)(UGQ + tok * 2048 + 1024 + h * HD + ch * 8) = pg8::pack8(a0, a1);
;     }
.LBB0_456:
	s_mulk_i32 s33, 0x1e00
	s_add_i32 s20, s20, s33
	v_mul_u32_u24_e32 v32, 0x110, v106
	v_add3_u32 v32, s20, v32, v64
	ds_write_b128 v32, v[16:19] offset:34816
	ds_write_b128 v32, v[0:3] offset:34944
	ds_write_b128 v32, v[20:23] offset:34848
	ds_write_b128 v32, v[4:7] offset:34976
	ds_write_b128 v32, v[24:27] offset:34880
	ds_write_b128 v32, v[8:11] offset:35008
	ds_write_b128 v32, v[28:31] offset:34912
	ds_write_b128 v32, v[12:15] offset:35040
	v_lshlrev_b32_e32 v0, 3, v104
	v_lshrrev_b32_e32 v8, 3, v105
	v_and_b32_e32 v0, 56, v0
	v_lshlrev_b32_e32 v1, 2, v0
	v_lshlrev_b32_e32 v64, 1, v0
	v_mul_u32_u24_e32 v0, 0x110, v8
	v_or_b32_e32 v8, s10, v8
	v_mov_b32_e32 v9, s11
	v_lshl_add_u64 v[10:11], s[14:15], 0, v[64:65]
	v_lshlrev_b64 v[12:13], 11, v[8:9]
	s_waitcnt lgkmcnt(0)
	v_add3_u32 v14, s20, v1, v0
	v_lshl_add_u64 v[12:13], v[10:11], 0, v[12:13]
	ds_read_b128 v[0:3], v14 offset:34816
	ds_read_b128 v[4:7], v14 offset:34832
	v_mov_b32_e32 v16, v128
	v_mov_b32_e32 v17, v129
	v_mov_b32_e32 v18, v130
	v_mov_b32_e32 v19, v131
	s_mov_b64 s[4:5], 0
	s_and_b64 vcc, exec, s[28:29]
	v_lshlrev_b32_e32 v12, 16, v16
	v_mul_f32_e32 v15, 0xbfb8aa3b, v12
	v_exp_f32_e32 v15, v15
	v_and_b32_e32 v13, 0xffff0000, v16
	v_add_f32_e32 v15, 1.0, v15
	v_rcp_f32_e32 v20, v15
	v_mul_f32_e32 v15, 0xbfb8aa3b, v13
	v_exp_f32_e32 v15, v15
	s_nop 0
	v_add_f32_e32 v15, 1.0, v15
	v_rcp_f32_e32 v21, v15
	s_nop 0
	v_pk_mul_f32 v[12:13], v[20:21], v[12:13]
	s_waitcnt lgkmcnt(1)
	v_pk_mul_f32 v[0:1], v[0:1], v[12:13]
	v_lshlrev_b32_e32 v12, 16, v18
	v_mul_f32_e32 v15, 0xbfb8aa3b, v12
	v_exp_f32_e32 v15, v15
	v_and_b32_e32 v13, 0xffff0000, v18
	v_cvt_pk_bf16_f32 v0, v0, v1
	v_add_f32_e32 v15, 1.0, v15
	v_rcp_f32_e32 v20, v15
	v_mul_f32_e32 v15, 0xbfb8aa3b, v13
	v_exp_f32_e32 v15, v15
	s_nop 0
	v_add_f32_e32 v15, 1.0, v15
	v_rcp_f32_e32 v21, v15
	s_nop 0
	v_pk_mul_f32 v[12:13], v[20:21], v[12:13]
	s_waitcnt lgkmcnt(0)
	v_pk_mul_f32 v[4:5], v[4:5], v[12:13]
	v_lshlrev_b32_e32 v12, 16, v17
	v_mul_f32_e32 v15, 0xbfb8aa3b, v12
	v_exp_f32_e32 v15, v15
	v_and_b32_e32 v13, 0xffff0000, v17
	v_add_f32_e32 v15, 1.0, v15
	v_rcp_f32_e32 v16, v15
	v_mul_f32_e32 v15, 0xbfb8aa3b, v13
	v_exp_f32_e32 v15, v15
	s_nop 0
	v_add_f32_e32 v15, 1.0, v15
	v_rcp_f32_e32 v17, v15
	s_nop 0
	v_pk_mul_f32 v[12:13], v[16:17], v[12:13]
	s_nop 0
	v_pk_mul_f32 v[2:3], v[2:3], v[12:13]
	v_lshlrev_b32_e32 v12, 16, v19
	v_mul_f32_e32 v15, 0xbfb8aa3b, v12
	v_exp_f32_e32 v15, v15
	v_and_b32_e32 v13, 0xffff0000, v19
	v_cvt_pk_bf16_f32 v1, v2, v3
	v_cvt_pk_bf16_f32 v2, v4, v5
	v_add_f32_e32 v15, 1.0, v15
	v_rcp_f32_e32 v16, v15
	v_mul_f32_e32 v15, 0xbfb8aa3b, v13
	v_exp_f32_e32 v15, v15
	v_lshlrev_b64 v[4:5], 12, v[8:9]
	v_lshl_add_u64 v[4:5], s[30:31], 0, v[4:5]
	v_lshl_add_u64 v[4:5], v[4:5], 0, v[64:65]
	v_add_f32_e32 v15, 1.0, v15
	v_rcp_f32_e32 v17, v15
	s_nop 0
	v_pk_mul_f32 v[12:13], v[16:17], v[12:13]
	s_nop 0
	v_pk_mul_f32 v[6:7], v[6:7], v[12:13]
	v_or_b32_e32 v12, 8, v8
	v_mov_b32_e32 v13, s11
	v_cvt_pk_bf16_f32 v3, v6, v7
	v_lshlrev_b64 v[16:17], 11, v[12:13]
	global_store_dwordx4 v[4:5], v[0:3], off offset:2048
	v_lshl_add_u64 v[16:17], v[10:11], 0, v[16:17]
	ds_read_b128 v[4:7], v14 offset:36992
	ds_read_b128 v[0:3], v14 offset:37008
	v_mov_b32_e32 v16, v132
	v_mov_b32_e32 v17, v133
	v_mov_b32_e32 v18, v134
	v_mov_b32_e32 v19, v135
	v_lshlrev_b32_e32 v20, 16, v16
	v_mul_f32_e32 v15, 0xbfb8aa3b, v20
	v_exp_f32_e32 v15, v15
	v_and_b32_e32 v21, 0xffff0000, v16
	v_add_f32_e32 v15, 1.0, v15
	v_rcp_f32_e32 v22, v15
	v_mul_f32_e32 v15, 0xbfb8aa3b, v21
	v_exp_f32_e32 v15, v15
	s_nop 0
	v_add_f32_e32 v15, 1.0, v15
	v_rcp_f32_e32 v23, v15
	s_nop 0
	v_pk_mul_f32 v[20:21], v[22:23], v[20:21]
	s_waitcnt lgkmcnt(1)
	v_pk_mul_f32 v[4:5], v[4:5], v[20:21]
	v_lshlrev_b32_e32 v20, 16, v18
	v_mul_f32_e32 v15, 0xbfb8aa3b, v20
	v_exp_f32_e32 v15, v15
	v_and_b32_e32 v21, 0xffff0000, v18
	v_add_f32_e32 v15, 1.0, v15
	v_rcp_f32_e32 v22, v15
	v_mul_f32_e32 v15, 0xbfb8aa3b, v21
	v_exp_f32_e32 v15, v15
	s_nop 0
	v_add_f32_e32 v15, 1.0, v15
	v_rcp_f32_e32 v23, v15
	s_nop 0
	v_pk_mul_f32 v[20:21], v[22:23], v[20:21]
	s_waitcnt lgkmcnt(0)
	v_pk_mul_f32 v[20:21], v[0:1], v[20:21]
	v_lshlrev_b32_e32 v0, 16, v17
	v_mul_f32_e32 v15, 0xbfb8aa3b, v0
	v_exp_f32_e32 v15, v15
	v_and_b32_e32 v1, 0xffff0000, v17
	v_add_f32_e32 v15, 1.0, v15
	v_rcp_f32_e32 v16, v15
	v_mul_f32_e32 v15, 0xbfb8aa3b, v1
	v_exp_f32_e32 v15, v15
	s_nop 0
	v_add_f32_e32 v15, 1.0, v15
	v_rcp_f32_e32 v17, v15
	s_nop 0
	v_pk_mul_f32 v[0:1], v[16:17], v[0:1]
	s_nop 0
	v_pk_mul_f32 v[6:7], v[6:7], v[0:1]
	v_lshlrev_b32_e32 v0, 16, v19
	v_mul_f32_e32 v15, 0xbfb8aa3b, v0
	v_exp_f32_e32 v15, v15
	v_and_b32_e32 v1, 0xffff0000, v19
	v_add_f32_e32 v15, 1.0, v15
	v_rcp_f32_e32 v16, v15
	v_mul_f32_e32 v15, 0xbfb8aa3b, v1
	v_exp_f32_e32 v15, v15
	s_nop 0
	v_add_f32_e32 v15, 1.0, v15
	v_rcp_f32_e32 v17, v15
	s_nop 0
	v_pk_mul_f32 v[0:1], v[16:17], v[0:1]
	s_nop 0
	v_pk_mul_f32 v[16:17], v[2:3], v[0:1]
	v_cvt_pk_bf16_f32 v0, v4, v5
	v_lshlrev_b64 v[4:5], 12, v[12:13]
	v_lshl_add_u64 v[4:5], s[30:31], 0, v[4:5]
	v_or_b32_e32 v12, 16, v8
	v_cvt_pk_bf16_f32 v1, v6, v7
	v_cvt_pk_bf16_f32 v2, v20, v21
	v_cvt_pk_bf16_f32 v3, v16, v17
	v_lshl_add_u64 v[4:5], v[4:5], 0, v[64:65]
	v_lshlrev_b64 v[16:17], 11, v[12:13]
	global_store_dwordx4 v[4:5], v[0:3], off offset:2048
	v_lshl_add_u64 v[16:17], v[10:11], 0, v[16:17]
	ds_read_b128 v[4:7], v14 offset:39168
	ds_read_b128 v[0:3], v14 offset:39184
	v_or_b32_e32 v8, 24, v8
	v_mov_b32_e32 v16, v136
	v_mov_b32_e32 v17, v137
	v_mov_b32_e32 v18, v138
	v_mov_b32_e32 v19, v139
	v_lshlrev_b32_e32 v20, 16, v16
	v_mul_f32_e32 v15, 0xbfb8aa3b, v20
	v_exp_f32_e32 v15, v15
	v_and_b32_e32 v21, 0xffff0000, v16
	v_add_f32_e32 v15, 1.0, v15
	v_rcp_f32_e32 v22, v15
	v_mul_f32_e32 v15, 0xbfb8aa3b, v21
	v_exp_f32_e32 v15, v15
	s_nop 0
	v_add_f32_e32 v15, 1.0, v15
	v_rcp_f32_e32 v23, v15
	s_nop 0
	v_pk_mul_f32 v[20:21], v[22:23], v[20:21]
	s_waitcnt lgkmcnt(1)
; __device__ __forceinline__ float sigm(float x) { return __builtin_amdgcn_rcpf(1.f + __builtin_amdgcn_exp2f(-1.4426950408889634f * x)); }
; __device__ __forceinline__ u32x4 pack8(const f32x4 a, const f32x4 b) { u32x4 w; w.x = cvt_pk_bf16(a[0], a[1]); w.y = cvt_pk_bf16(a[2], a[3]); w.z = cvt_pk_bf16(b[0], b[1]); w.w = cvt_pk_bf16(b[2], b[3]); return w; }
; #define LAS __attribute__((address_space(3)))
;     ...
;     for (int i = 0; i < 4; ++i) {
;         const int row = i * 8 + (lane >> 3), ch = lane & 7;
;         f32x4 a0 = *(const LAS f32x4*)(stg + row * 68 + ch * 8), a1 = *(const LAS f32x4*)(stg + row * 68 + ch * 8 + 4);
;         const size_t tok = rowbase + qw + row;
;         const u32x4 gw_ = *(const u32x4*)(GBb + tok * 1024 + h * HD + ch * 8);
;         f32x4 g0, g1; pg8::unpack8(gw_, g0, g1);
; #pragma unroll
;         for (int e = 0; e < 4; ++e) { a0[e] *= g0[e] * pg8::sigm(g0[e]); a1[e] *= g1[e] * pg8::sigm(g1[e]); }
;         if (!dry) *(u32x4*)(UGQ + tok * 2048 + 1024 + h * HD + ch * 8) = pg8::pack8(a0, a1);
;     }
	v_pk_mul_f32 v[4:5], v[4:5], v[20:21]
	v_lshlrev_b32_e32 v20, 16, v18
	v_mul_f32_e32 v15, 0xbfb8aa3b, v20
	v_exp_f32_e32 v15, v15
	v_and_b32_e32 v21, 0xffff0000, v18
	v_add_f32_e32 v15, 1.0, v15
	v_rcp_f32_e32 v22, v15
	v_mul_f32_e32 v15, 0xbfb8aa3b, v21
	v_exp_f32_e32 v15, v15
	s_nop 0
	v_add_f32_e32 v15, 1.0, v15
	v_rcp_f32_e32 v23, v15
	s_nop 0
	v_pk_mul_f32 v[20:21], v[22:23], v[20:21]
	s_waitcnt lgkmcnt(0)
	v_pk_mul_f32 v[20:21], v[0:1], v[20:21]
	v_lshlrev_b32_e32 v0, 16, v17
	v_mul_f32_e32 v15, 0xbfb8aa3b, v0
	v_exp_f32_e32 v15, v15
	v_and_b32_e32 v1, 0xffff0000, v17
	v_add_f32_e32 v15, 1.0, v15
	v_rcp_f32_e32 v16, v15
	v_mul_f32_e32 v15, 0xbfb8aa3b, v1
	v_exp_f32_e32 v15, v15
	s_nop 0
	v_add_f32_e32 v15, 1.0, v15
	v_rcp_f32_e32 v17, v15
	s_nop 0
	v_pk_mul_f32 v[0:1], v[16:17], v[0:1]
	s_nop 0
	v_pk_mul_f32 v[6:7], v[6:7], v[0:1]
	v_lshlrev_b32_e32 v0, 16, v19
	v_mul_f32_e32 v15, 0xbfb8aa3b, v0
	v_exp_f32_e32 v15, v15
	v_and_b32_e32 v1, 0xffff0000, v19
	v_add_f32_e32 v15, 1.0, v15
	v_rcp_f32_e32 v16, v15
	v_mul_f32_e32 v15, 0xbfb8aa3b, v1
	v_exp_f32_e32 v15, v15
	s_nop 0
	v_add_f32_e32 v15, 1.0, v15
	v_rcp_f32_e32 v17, v15
	s_nop 0
	v_pk_mul_f32 v[0:1], v[16:17], v[0:1]
	s_nop 0
	v_pk_mul_f32 v[16:17], v[2:3], v[0:1]
	v_cvt_pk_bf16_f32 v0, v4, v5
	v_lshlrev_b64 v[4:5], 12, v[12:13]
	v_lshl_add_u64 v[4:5], s[30:31], 0, v[4:5]
	v_cvt_pk_bf16_f32 v1, v6, v7
	v_cvt_pk_bf16_f32 v2, v20, v21
	v_cvt_pk_bf16_f32 v3, v16, v17
	v_lshl_add_u64 v[4:5], v[4:5], 0, v[64:65]
	v_lshlrev_b64 v[12:13], 11, v[8:9]
	global_store_dwordx4 v[4:5], v[0:3], off offset:2048
	v_lshl_add_u64 v[10:11], v[10:11], 0, v[12:13]
	ds_read_b128 v[4:7], v14 offset:41344
	ds_read_b128 v[0:3], v14 offset:41360
	v_mov_b32_e32 v10, v164
	v_mov_b32_e32 v11, v165
	v_mov_b32_e32 v12, v166
	v_mov_b32_e32 v13, v167
	v_lshlrev_b32_e32 v14, 16, v10
	v_and_b32_e32 v15, 0xffff0000, v10
	v_mul_f32_e32 v10, 0xbfb8aa3b, v14
	v_exp_f32_e32 v10, v10
	s_nop 0
	v_add_f32_e32 v10, 1.0, v10
	v_rcp_f32_e32 v16, v10
	v_mul_f32_e32 v10, 0xbfb8aa3b, v15
	v_exp_f32_e32 v10, v10
	s_nop 0
	v_add_f32_e32 v10, 1.0, v10
	v_rcp_f32_e32 v17, v10
	s_nop 0
	v_pk_mul_f32 v[14:15], v[16:17], v[14:15]
	s_waitcnt lgkmcnt(1)
	v_pk_mul_f32 v[4:5], v[4:5], v[14:15]
	v_lshlrev_b32_e32 v14, 16, v12
	v_mul_f32_e32 v10, 0xbfb8aa3b, v14
	v_exp_f32_e32 v10, v10
	v_and_b32_e32 v15, 0xffff0000, v12
	v_add_f32_e32 v10, 1.0, v10
	v_rcp_f32_e32 v16, v10
	v_mul_f32_e32 v10, 0xbfb8aa3b, v15
	v_exp_f32_e32 v10, v10
	s_nop 0
	v_add_f32_e32 v10, 1.0, v10
	v_rcp_f32_e32 v17, v10
	s_nop 0
	v_pk_mul_f32 v[14:15], v[16:17], v[14:15]
	s_waitcnt lgkmcnt(0)
	v_pk_mul_f32 v[14:15], v[0:1], v[14:15]
	v_lshlrev_b32_e32 v0, 16, v11
	v_and_b32_e32 v1, 0xffff0000, v11
	v_mul_f32_e32 v10, 0xbfb8aa3b, v0
	v_mul_f32_e32 v11, 0xbfb8aa3b, v1
	v_exp_f32_e32 v10, v10
	v_exp_f32_e32 v11, v11
	v_add_f32_e32 v10, 1.0, v10
	v_add_f32_e32 v11, 1.0, v11
	v_rcp_f32_e32 v10, v10
	v_rcp_f32_e32 v11, v11
	s_nop 0
	v_pk_mul_f32 v[0:1], v[10:11], v[0:1]
	s_nop 0
	v_pk_mul_f32 v[6:7], v[6:7], v[0:1]
	v_lshlrev_b32_e32 v0, 16, v13
	v_and_b32_e32 v1, 0xffff0000, v13
	v_mul_f32_e32 v10, 0xbfb8aa3b, v0
	v_mul_f32_e32 v11, 0xbfb8aa3b, v1
	v_exp_f32_e32 v10, v10
	v_exp_f32_e32 v11, v11
	v_add_f32_e32 v10, 1.0, v10
	v_add_f32_e32 v11, 1.0, v11
	v_rcp_f32_e32 v10, v10
	v_rcp_f32_e32 v11, v11
	s_nop 0
	v_pk_mul_f32 v[0:1], v[10:11], v[0:1]
	s_nop 0
	v_pk_mul_f32 v[10:11], v[2:3], v[0:1]
	v_cvt_pk_bf16_f32 v0, v4, v5
	v_lshlrev_b64 v[4:5], 12, v[8:9]
	v_lshl_add_u64 v[4:5], s[30:31], 0, v[4:5]
	v_cvt_pk_bf16_f32 v1, v6, v7
	v_cvt_pk_bf16_f32 v2, v14, v15
	v_cvt_pk_bf16_f32 v3, v10, v11
	v_lshl_add_u64 v[4:5], v[4:5], 0, v[64:65]
	global_store_dwordx4 v[4:5], v[0:3], off offset:2048
	s_waitcnt lgkmcnt(0)
	s_cbranch_vccnz .LBB0_454
; #define LAS __attribute__((address_space(3)))
;     ...
;     const int tid = tid_, lane = tid & 63, wid = __builtin_amdgcn_readfirstlane(tid >> 6), r32 = lane & 31, hi = lane >> 5;
;     const size_t rowbase = (size_t)b * SEQ;
;     const int q0 = qb * 256, qw = q0 + wid * 32;
;     bf16x8 qr[4];
;     { const bf16* qp = UGQ + (rowbase + qw + r32) * 2048 + 1024 + h * HD + hi * 8;
; #pragma unroll
;       for (int d0 = 0; d0 < 4; ++d0) qr[d0] = *(const bf16x8*)(qp + d0 * 16); }
;     f32x16 o0, o1;
; #pragma unroll
;     for (int r = 0; r < 16; ++r) { o0[r] = 0.f; o1[r] = 0.f; }
;     float C = 1.f; int alive = 1;
;     volatile LAS unsigned* aflag = (volatile LAS unsigned*)(lds + RING_BYTES);
;     const int NT = 4 * (qb + 1);
;     const int lkey = lane, lch = wid;
;     const int kk = lkey & 31, slot = (lkey & 32) | (8 * ((kk >> 2) & 3) + 4 * (kk >> 4) + (kk & 3));
;     const bf16* kg = Kb + (rowbase + lkey) * 1024 + h * HD + lch * 8;
;     const bf16* vg = Vb + (rowbase + lkey) * 1024 + h * HD + lch * 8;
;     u32x4 kreg, vreg;
;     kreg = *(const u32x4*)(kg + (size_t)(NT - 1) * 64 * 1024); vreg = *(const u32x4*)(vg + (size_t)(NT - 1) * 64 * 1024);
;     ...
;     AT_WRITE(0);
;     __syncthreads();
;     ...
;         const u32x4 gw_ = *(const u32x4*)(GBb + tok * 1024 + h * HD + ch * 8);
.LBB0_457:
	s_xor_b64 s[28:29], s[4:5], -1
	s_and_b64 s[4:5], s[4:5], exec
	v_readlane_b32 s1, v255, 48
	v_mov_b32_e32 v104, v232
	s_cselect_b32 s6, s1, s0
	v_readlane_b32 s12, v254, 58
	v_readfirstlane_b32 s1, v104
	s_ashr_i32 s33, s1, 6
	s_lshl_b32 s1, s6, 8
	s_lshl_b32 s24, s33, 5
	s_add_i32 s24, s24, s1
	s_ashr_i32 s4, s24, 31
	s_add_u32 s10, s18, s24
	v_and_b32_e32 v106, 31, v104
	s_addc_u32 s11, s19, s4
	v_or_b32_e32 v0, s10, v106
	v_mov_b32_e32 v1, s11
	v_bfe_u32 v4, v104, 5, 1
	v_lshlrev_b64 v[0:1], 12, v[0:1]
	v_lshl_add_u64 v[0:1], s[30:31], 0, v[0:1]
	v_lshlrev_b32_e32 v64, 4, v4
	v_lshl_add_u64 v[0:1], v[0:1], 0, v[64:65]
	global_load_dwordx4 v[66:69], v[0:1], off offset:2048
	global_load_dwordx4 v[70:73], v[0:1], off offset:2080
	global_load_dwordx4 v[74:77], v[0:1], off offset:2112
	global_load_dwordx4 v[78:81], v[0:1], off offset:2144
	v_lshlrev_b32_e32 v0, 1, v104
	v_lshrrev_b32_e32 v1, 2, v104
	v_and_b32_e32 v105, 63, v104
	v_lshlrev_b32_e32 v114, 3, v104
	v_lshrrev_b32_e32 v116, 3, v105
	v_and_b32_e32 v114, 56, v114
	v_or_b32_e32 v116, s10, v116
	v_mov_b32_e32 v117, s11
	v_lshlrev_b32_e32 v114, 1, v114
	v_mov_b32_e32 v115, 0
	v_lshlrev_b64 v[116:117], 11, v[116:117]
	v_lshl_add_u64 v[114:115], s[14:15], 0, v[114:115]
	s_mov_b64 s[100:101], 0x4000
	v_lshl_add_u64 v[114:115], v[114:115], 0, v[116:117]
	global_load_dwordx4 v[128:131], v[114:115], off
	v_lshl_add_u64 v[116:117], v[114:115], 0, s[100:101]
	global_load_dwordx4 v[132:135], v[116:117], off
	v_lshl_add_u64 v[116:117], s[100:101], 1, v[114:115]
	global_load_dwordx4 v[136:139], v[116:117], off
	v_lshl_add_u64 v[116:117], v[116:117], 0, s[100:101]
	global_load_dwordx4 v[164:167], v[116:117], off
	v_and_b32_e32 v0, 24, v0
	v_and_b32_e32 v1, 4, v1
	v_and_b32_e32 v2, 35, v104
	v_or3_b32 v5, v2, v1, v0
	v_or_b32_e32 v0, s18, v105
	v_mov_b32_e32 v1, s19
	v_readlane_b32 s4, v255, 49
	v_lshlrev_b64 v[0:1], 11, v[0:1]
	v_readlane_b32 s5, v255, 50
	s_lshl_b32 s7, s6, 19
	v_readlane_b32 s13, v254, 59
	v_lshl_add_u64 v[2:3], s[4:5], 0, v[0:1]
	s_lshl_b32 s4, s33, 3
	s_ashr_i32 s5, s4, 31
	s_lshl_b64 s[4:5], s[4:5], 1
	v_lshl_add_u64 v[0:1], s[8:9], 0, v[0:1]
	v_lshl_add_u64 v[2:3], v[2:3], 0, s[4:5]
	v_lshl_add_u64 v[0:1], v[0:1], 0, s[4:5]
	s_mov_b32 s21, s13
	s_or_b32 s20, s7, 0x60000
	v_lshl_add_u64 v[2:3], v[2:3], 0, s[20:21]
	v_lshl_add_u64 v[0:1], v[0:1], 0, s[20:21]
	global_load_dwordx4 v[82:85], v[2:3], off
	global_load_dwordx4 v[86:89], v[0:1], off
	s_lshl_b32 s25, s6, 2
	s_lshl_b32 s6, s33, 10
	v_writelane_b32 v254, s12, 58
	s_add_i32 s20, s6, 0
	s_mul_i32 s6, s33, 0x480
	v_writelane_b32 v254, s13, 59
	s_add_i32 s6, s6, 0
	v_lshl_add_u32 v108, v105, 1, s6
	s_lshl_b32 s6, s33, 2
	v_readlane_b32 s12, v254, 57
	s_add_i32 s25, s25, 4
	s_add_i32 s26, s12, s6
	v_lshlrev_b32_e32 v0, 10, v4
	v_lshlrev_b32_e32 v1, 4, v106
	v_add3_u32 v111, 0, v0, v1
	v_mul_u32_u24_e32 v0, 0x90, v106
	v_and_b32_e32 v1, 32, v104
	s_add_u32 s4, s4, s7
	v_add3_u32 v112, 0, v0, v1
	v_lshlrev_b32_e32 v0, 11, v105
	v_mov_b32_e32 v1, v65
	s_addc_u32 s5, s5, 0
	v_lshl_add_u64 v[0:1], s[4:5], 0, v[0:1]
	v_mov_b32_e32 v14, v65
	v_mov_b32_e32 v15, v65
	v_lshl_add_u32 v107, v5, 4, s20
	v_lshl_add_u64 v[90:91], s[34:35], 0, v[0:1]
	v_lshl_add_u64 v[92:93], s[2:3], 0, v[0:1]
	v_mov_b32_e32 v0, v65
	v_mov_b32_e32 v1, v65
	v_mov_b32_e32 v2, v65
	v_mov_b32_e32 v3, v65
	v_mov_b32_e32 v4, v65
	v_mov_b32_e32 v5, v65
	v_mov_b32_e32 v6, v65
	v_mov_b32_e32 v7, v65
	v_mov_b32_e32 v8, v65
	v_mov_b32_e32 v9, v65
	v_mov_b32_e32 v10, v65
	v_mov_b32_e32 v11, v65
	v_mov_b32_e32 v12, v65
	v_mov_b32_e32 v13, v65
	v_mov_b64_e32 v[30:31], v[14:15]
	v_or_b32_e32 v109, s24, v106
	v_lshl_add_u32 v110, v105, 2, s12
	v_cmp_gt_u32_e64 s[36:37], 32, v105
	s_mov_b32 s6, 0
	v_cmp_eq_u32_e64 s[38:39], 0, v105
	v_cmp_gt_u32_e64 s[40:41], 8, v105
	s_or_b32 s27, s1, 0xc0
	v_mov_b32_e32 v95, 1.0
	v_mov_b32_e32 v32, 1
	v_mov_b64_e32 v[28:29], v[12:13]
	v_mov_b64_e32 v[26:27], v[10:11]
	v_mov_b64_e32 v[24:25], v[8:9]
	v_mov_b64_e32 v[22:23], v[6:7]
	v_mov_b64_e32 v[20:21], v[4:5]
	v_mov_b64_e32 v[18:19], v[2:3]
	v_mov_b64_e32 v[16:17], v[0:1]
	s_waitcnt vmcnt(1)
	ds_write_b128 v107, v[82:85]
	s_waitcnt vmcnt(0)
	ds_write_b16 v108, v86 offset:16384
	ds_write_b16_d16_hi v108, v86 offset:16528
	ds_write_b16 v108, v87 offset:16672
	ds_write_b16_d16_hi v108, v87 offset:16816
	ds_write_b16 v108, v88 offset:16960
	ds_write_b16_d16_hi v108, v88 offset:17104
	ds_write_b16 v108, v89 offset:17248
	ds_write_b16_d16_hi v108, v89 offset:17392
	s_waitcnt lgkmcnt(0)
	s_barrier
	s_cmpk_eq_i32 s27, 0xffc0
	s_cbranch_scc0 .LBB0_459
